# G1 epilogue qk-RMSNorm: 8-lane sum of squares by three DPP adds (quad_perm, row_half_mirror) instead of three ds_bpermute round trips
# speedup vs baseline: 1.0010x; 1.0010x over previous
.LBB0_709:
	ds_read_b128 v[134:137], v184
	ds_read_b128 v[130:133], v184 offset:128
	s_and_saveexec_b64 s[28:29], s[20:21]
	s_cbranch_execz .LBB0_711
	s_waitcnt lgkmcnt(1)
	v_pk_mul_f32 v[162:163], v[134:135], v[134:135]
	v_pk_mul_f32 v[188:189], v[136:137], v[136:137]
	v_add_f32_e32 v0, v162, v163
	v_add_f32_e32 v0, v0, v188
	s_waitcnt lgkmcnt(0)
	v_pk_mul_f32 v[190:191], v[130:131], v[130:131]
	v_add_f32_e32 v0, v0, v189
	v_add_f32_e32 v0, v0, v190
	v_pk_mul_f32 v[192:193], v[132:133], v[132:133]
	v_add_f32_e32 v0, v0, v191
	v_add_f32_e32 v0, v0, v192
	v_add_f32_e32 v0, v0, v193
	s_nop 1
	v_add_f32_dpp v0, v0, v0 quad_perm:[1,0,3,2] row_mask:0xf bank_mask:0xf
	s_nop 1
	v_add_f32_dpp v0, v0, v0 quad_perm:[2,3,0,1] row_mask:0xf bank_mask:0xf
	s_nop 1
	v_add_f32_dpp v0, v0, v0 row_half_mirror row_mask:0xf bank_mask:0xf
	s_nop 1
	v_fmamk_f32 v0, v0, 0x3c800000, v205
	v_cmp_gt_f32_e32 vcc, s33, v0
	v_mul_f32_e32 v145, 0x4b800000, v0
	s_nop 0
	v_cndmask_b32_e32 v0, v0, v145, vcc
	v_rsq_f32_e32 v0, v0
	s_nop 0
	v_mul_f32_e32 v145, 0x45800000, v0
	v_cndmask_b32_e32 v0, v0, v145, vcc
	s_waitcnt vmcnt(4)
	v_pk_mul_f32 v[162:163], v[232:233], v[0:1] op_sel_hi:[1,0]
	s_nop 0
	v_pk_mul_f32 v[134:135], v[134:135], v[162:163]
	s_waitcnt vmcnt(4)
	v_pk_mul_f32 v[162:163], v[236:237], v[0:1] op_sel_hi:[1,0]
	s_nop 0
	v_pk_mul_f32 v[130:131], v[130:131], v[162:163]
	v_pk_mul_f32 v[162:163], v[234:235], v[0:1] op_sel_hi:[1,0]
	s_nop 0
	v_pk_mul_f32 v[136:137], v[136:137], v[162:163]
	v_pk_mul_f32 v[162:163], v[238:239], v[0:1] op_sel_hi:[1,0]
	s_nop 0
	v_pk_mul_f32 v[132:133], v[132:133], v[162:163]
	s_or_b64 exec, exec, s[28:29]
	s_and_saveexec_b64 s[28:29], s[40:41]
	s_cbranch_execz .LBB0_713
	s_branch .LBB0_712

.LBB0_768:
	ds_read_b128 v[134:137], v141
	ds_read_b128 v[130:133], v141 offset:128
	s_and_saveexec_b64 s[28:29], s[20:21]
	s_cbranch_execz .LBB0_770
	s_waitcnt lgkmcnt(1)
	v_pk_mul_f32 v[160:161], v[134:135], v[134:135]
	v_pk_mul_f32 v[166:167], v[136:137], v[136:137]
	v_add_f32_e32 v0, v160, v161
	v_add_f32_e32 v0, v0, v166
	s_waitcnt lgkmcnt(0)
	v_pk_mul_f32 v[170:171], v[130:131], v[130:131]
	v_add_f32_e32 v0, v0, v167
	v_add_f32_e32 v0, v0, v170
	v_pk_mul_f32 v[172:173], v[132:133], v[132:133]
	v_add_f32_e32 v0, v0, v171
	v_add_f32_e32 v0, v0, v172
	v_add_f32_e32 v0, v0, v173
	s_nop 1
	v_add_f32_dpp v0, v0, v0 quad_perm:[1,0,3,2] row_mask:0xf bank_mask:0xf
	s_nop 1
	v_add_f32_dpp v0, v0, v0 quad_perm:[2,3,0,1] row_mask:0xf bank_mask:0xf
	s_nop 1
	v_add_f32_dpp v0, v0, v0 row_half_mirror row_mask:0xf bank_mask:0xf
	s_nop 1
	v_fmamk_f32 v0, v0, 0x3c800000, v205
	v_cmp_gt_f32_e32 vcc, s33, v0
	v_mul_f32_e32 v160, 0x4b800000, v0
	s_nop 0
	v_cndmask_b32_e32 v0, v0, v160, vcc
	v_rsq_f32_e32 v0, v0
	s_nop 0
	v_mul_f32_e32 v160, 0x45800000, v0
	v_cndmask_b32_e32 v0, v0, v160, vcc
	s_waitcnt vmcnt(4)
	v_pk_mul_f32 v[160:161], v[232:233], v[0:1] op_sel_hi:[1,0]
	s_nop 0
	v_pk_mul_f32 v[134:135], v[134:135], v[160:161]
	s_waitcnt vmcnt(4)
	v_pk_mul_f32 v[160:161], v[236:237], v[0:1] op_sel_hi:[1,0]
	s_nop 0
	v_pk_mul_f32 v[130:131], v[130:131], v[160:161]
	v_pk_mul_f32 v[160:161], v[234:235], v[0:1] op_sel_hi:[1,0]
	s_nop 0
	v_pk_mul_f32 v[136:137], v[136:137], v[160:161]
	v_pk_mul_f32 v[160:161], v[238:239], v[0:1] op_sel_hi:[1,0]
	s_nop 0
	v_pk_mul_f32 v[132:133], v[132:133], v[160:161]
	s_or_b64 exec, exec, s[28:29]
	s_and_saveexec_b64 s[28:29], s[40:41]
	s_cbranch_execz .LBB0_772
	s_branch .LBB0_771
